# retention PV segment opens with MFMAs: second-half P conversion moved behind the third MFMA, head s_nop removed
# baseline (speedup 1.0000x reference)
.LBB0_863:
	s_waitcnt lgkmcnt(12)
	v_mfma_f32_16x16x32_bf16 v[70:73], v[116:119], v[0:3], v[70:73]
	ds_read_b64_tr_b16 v[116:117], v114
	ds_read_b64_tr_b16 v[118:119], v114 offset:8192
	s_waitcnt lgkmcnt(12)
	v_mfma_f32_16x16x32_bf16 v[66:69], v[120:123], v[0:3], v[66:69]
	ds_read_b64_tr_b16 v[120:121], v115 offset:256
	ds_read_b64_tr_b16 v[122:123], v115 offset:8448
	s_waitcnt lgkmcnt(12)
	v_mfma_f32_16x16x32_bf16 v[62:65], v[124:127], v[0:3], v[62:65]
	ds_read_b64_tr_b16 v[124:125], v108 offset:256
	ds_read_b64_tr_b16 v[126:127], v108 offset:8448
	v_cvt_pk_bf16_f32 v6, v174, v175
	v_cvt_pk_bf16_f32 v7, v176, v177
	s_waitcnt lgkmcnt(12)
	v_mfma_f32_16x16x32_bf16 v[58:61], v[128:131], v[0:3], v[58:61]
	ds_read_b64_tr_b16 v[128:129], v109 offset:256
	ds_read_b64_tr_b16 v[130:131], v109 offset:8448
	s_waitcnt lgkmcnt(12)
	v_mfma_f32_16x16x32_bf16 v[54:57], v[210:213], v[0:3], v[54:57]
	ds_read_b64_tr_b16 v[210:211], v110 offset:256
	ds_read_b64_tr_b16 v[212:213], v110 offset:8448
	s_waitcnt lgkmcnt(12)
	v_mfma_f32_16x16x32_bf16 v[50:53], v[202:205], v[0:3], v[50:53]
	ds_read_b64_tr_b16 v[202:203], v111 offset:256
	ds_read_b64_tr_b16 v[204:205], v111 offset:8448
	s_waitcnt lgkmcnt(12)
	v_mfma_f32_16x16x32_bf16 v[46:49], v[206:209], v[0:3], v[46:49]
	ds_read_b64_tr_b16 v[206:207], v112 offset:256
	ds_read_b64_tr_b16 v[208:209], v112 offset:8448
	s_waitcnt lgkmcnt(12)
	v_mfma_f32_16x16x32_bf16 v[42:45], v[116:119], v[0:3], v[42:45]
	ds_read_b64_tr_b16 v[116:117], v113 offset:256
	ds_read_b64_tr_b16 v[118:119], v113 offset:8448
	s_waitcnt lgkmcnt(12)
	v_mfma_f32_16x16x32_bf16 v[38:41], v[120:123], v[0:3], v[38:41]
	ds_read_b64_tr_b16 v[120:121], v114 offset:256
	ds_read_b64_tr_b16 v[122:123], v114 offset:8448
	s_waitcnt lgkmcnt(12)
	v_mfma_f32_16x16x32_bf16 v[34:37], v[124:127], v[0:3], v[34:37]
	ds_read_b64_tr_b16 v[124:125], v115 offset:16384
	ds_read_b64_tr_b16 v[126:127], v115 offset:24576
	s_waitcnt lgkmcnt(12)
	v_mfma_f32_16x16x32_bf16 v[30:33], v[128:131], v[0:3], v[30:33]
	ds_read_b64_tr_b16 v[128:129], v108 offset:16384
	ds_read_b64_tr_b16 v[130:131], v108 offset:24576
	s_waitcnt lgkmcnt(12)
	v_mfma_f32_16x16x32_bf16 v[26:29], v[210:213], v[0:3], v[26:29]
	ds_read_b64_tr_b16 v[210:211], v109 offset:16384
	ds_read_b64_tr_b16 v[212:213], v109 offset:24576
	s_waitcnt lgkmcnt(12)
	v_mfma_f32_16x16x32_bf16 v[22:25], v[202:205], v[0:3], v[22:25]
	ds_read_b64_tr_b16 v[202:203], v110 offset:16384
	ds_read_b64_tr_b16 v[204:205], v110 offset:24576
	s_waitcnt lgkmcnt(12)
	v_mfma_f32_16x16x32_bf16 v[18:21], v[206:209], v[0:3], v[18:21]
	ds_read_b64_tr_b16 v[206:207], v111 offset:16384
	ds_read_b64_tr_b16 v[208:209], v111 offset:24576
	s_waitcnt lgkmcnt(12)
	v_mfma_f32_16x16x32_bf16 v[14:17], v[116:119], v[0:3], v[14:17]
	ds_read_b64_tr_b16 v[116:117], v112 offset:16384
	ds_read_b64_tr_b16 v[118:119], v112 offset:24576
	s_waitcnt lgkmcnt(12)
	v_mfma_f32_16x16x32_bf16 v[10:13], v[120:123], v[0:3], v[10:13]
	ds_read_b64_tr_b16 v[120:121], v113 offset:16384
	ds_read_b64_tr_b16 v[122:123], v113 offset:24576
	s_waitcnt lgkmcnt(12)
	v_mfma_f32_16x16x32_bf16 v[70:73], v[124:127], v[4:7], v[70:73]
	ds_read_b64_tr_b16 v[124:125], v114 offset:16384
	ds_read_b64_tr_b16 v[126:127], v114 offset:24576
	s_waitcnt lgkmcnt(12)
	v_mfma_f32_16x16x32_bf16 v[66:69], v[128:131], v[4:7], v[66:69]
	ds_read_b64_tr_b16 v[128:129], v115 offset:16640
	ds_read_b64_tr_b16 v[130:131], v115 offset:24832
	s_waitcnt lgkmcnt(12)
	v_mfma_f32_16x16x32_bf16 v[62:65], v[210:213], v[4:7], v[62:65]
	ds_read_b64_tr_b16 v[210:211], v108 offset:16640
	ds_read_b64_tr_b16 v[212:213], v108 offset:24832
	s_waitcnt lgkmcnt(12)
	v_mfma_f32_16x16x32_bf16 v[58:61], v[202:205], v[4:7], v[58:61]
	ds_read_b64_tr_b16 v[202:203], v109 offset:16640
	ds_read_b64_tr_b16 v[204:205], v109 offset:24832
	s_waitcnt lgkmcnt(12)
	v_mfma_f32_16x16x32_bf16 v[54:57], v[206:209], v[4:7], v[54:57]
	ds_read_b64_tr_b16 v[206:207], v110 offset:16640
	ds_read_b64_tr_b16 v[208:209], v110 offset:24832
	s_waitcnt lgkmcnt(12)
	v_mfma_f32_16x16x32_bf16 v[50:53], v[116:119], v[4:7], v[50:53]
	ds_read_b64_tr_b16 v[116:117], v111 offset:16640
	ds_read_b64_tr_b16 v[118:119], v111 offset:24832
	s_waitcnt lgkmcnt(12)
	v_mfma_f32_16x16x32_bf16 v[46:49], v[120:123], v[4:7], v[46:49]
	ds_read_b64_tr_b16 v[120:121], v112 offset:16640
	ds_read_b64_tr_b16 v[122:123], v112 offset:24832
	s_waitcnt lgkmcnt(12)
	v_mfma_f32_16x16x32_bf16 v[42:45], v[124:127], v[4:7], v[42:45]
	ds_read_b64_tr_b16 v[124:125], v113 offset:16640
	ds_read_b64_tr_b16 v[126:127], v113 offset:24832
	s_waitcnt lgkmcnt(12)
	v_mfma_f32_16x16x32_bf16 v[38:41], v[128:131], v[4:7], v[38:41]
	ds_read_b64_tr_b16 v[128:129], v114 offset:16640
	ds_read_b64_tr_b16 v[130:131], v114 offset:24832
	s_waitcnt lgkmcnt(12)
	v_mfma_f32_16x16x32_bf16 v[34:37], v[210:213], v[4:7], v[34:37]
	s_waitcnt lgkmcnt(10)
	v_mfma_f32_16x16x32_bf16 v[30:33], v[202:205], v[4:7], v[30:33]
	s_waitcnt lgkmcnt(8)
	v_mfma_f32_16x16x32_bf16 v[26:29], v[206:209], v[4:7], v[26:29]
	s_waitcnt lgkmcnt(6)
	v_mfma_f32_16x16x32_bf16 v[22:25], v[116:119], v[4:7], v[22:25]
	s_waitcnt lgkmcnt(4)
	v_mfma_f32_16x16x32_bf16 v[18:21], v[120:123], v[4:7], v[18:21]
	s_waitcnt lgkmcnt(2)
	v_mfma_f32_16x16x32_bf16 v[14:17], v[124:127], v[4:7], v[14:17]
	s_waitcnt lgkmcnt(0)
	v_mfma_f32_16x16x32_bf16 v[10:13], v[128:131], v[4:7], v[10:13]
